# scan recurrence hand-scheduled: 40 pk ops + 12 dpp per step (no v_mov/xor, in-place decay)
# speedup vs baseline: 1.0231x; 1.0231x over previous
; #define LAS __attribute__((address_space(3)))
; __device__ __forceinline__ float red8(float v) { v += dppf<DPP_X1>(v); v += dppf<DPP_X2>(v); v += dppf<DPP_HM>(v); return v; }
;     ...
;             const LAS unsigned char* bp = lds + (ch & 1) * SC_BUF + kq * 32;
;             const LAS unsigned char* vvp = lds + (ch & 1) * SC_BUF + 40960 + 8 * vp;
;             struct StepV { f32x4 rr[2], ww[2], kx[2], qq[2], bb[2]; f32x2 vv; };
;     ...
;             StepV cur; SCAN_FETCH(cur, 0);
;             for (int t8 = 0; t8 < TC; t8 += 8) {
;                 f32x2 keep = {0.f, 0.f};
; #pragma unroll
;                 for (int j = 0; j < 8; ++j) {
;                     StepV nxt; { const int tn = (t8 + j + 1 < TC) ? t8 + j + 1 : t8 + j; SCAN_FETCH(nxt, tn); }
;                     asm volatile("" ::: "memory");
;                     f32x2 sa0 = S[0] * cur.qq[0][0] + S[1] * cur.qq[0][1], sa1 = S[2] * cur.qq[0][2] + S[3] * cur.qq[0][3], sa2 = S[4] * cur.qq[1][0] + S[5] * cur.qq[1][1], sa3 = S[6] * cur.qq[1][2] + S[7] * cur.qq[1][3];
;                     f32x2 tt[8];
; #pragma unroll
;                     for (int i = 0; i < 8; ++i) tt[i] = S[i] * cur.ww[i >> 2][i & 3] + cur.vv * cur.kx[i >> 2][i & 3];
;                     f32x2 sa = (sa0 + sa1) + (sa2 + sa3);
;                     { float sx = sa.x, sy = sa.y; asm volatile("" : "+v"(sx)); asm volatile("" : "+v"(sy)); sx = red8(sx); asm volatile("" : "+v"(sx)); sy = red8(sy); sa.x = -sx; sa.y = -sy; }
; #pragma unroll
;                     for (int i = 0; i < 8; ++i) S[i] = tt[i] + sa * cur.bb[i >> 2][i & 3];
;                     f32x2 oo = ((S[0] * cur.rr[0][0] + S[1] * cur.rr[0][1]) + (S[2] * cur.rr[0][2] + S[3] * cur.rr[0][3])) + ((S[4] * cur.rr[1][0] + S[5] * cur.rr[1][1]) + (S[6] * cur.rr[1][2] + S[7] * cur.rr[1][3]));
.LBB0_2838:
	s_and_b64 vcc, exec, s[18:19]
	s_cbranch_vccnz .LBB0_2841
	s_bitcmp1_b32 s22, 0
	s_cselect_b32 s1, 0xc000, 0
	v_add_u32_e32 v139, s1, v148
	v_add_u32_e32 v141, s1, v203
	v_mov_b32_e32 v180, v215
	ds_read_b128 v[82:85], v139 offset:24576
	ds_read_b128 v[86:89], v139 offset:24592
	ds_read_b128 v[66:69], v139 offset:8192
	ds_read_b128 v[70:73], v139 offset:8208
	ds_read_b128 v[74:77], v139 offset:16384
	ds_read_b128 v[78:81], v139 offset:16400
	ds_read_b64 v[98:99], v141 offset:40960
	ds_read_b128 v[90:93], v139 offset:32768
	ds_read_b128 v[94:97], v139 offset:32784
	ds_read_b128 v[58:61], v139
	ds_read_b128 v[62:65], v139 offset:16
	s_mov_b32 s24, 0
.Lscan4_loop:
	s_waitcnt lgkmcnt(0)
	ds_read_b128 v[124:127], v139 offset:24832
	ds_read_b128 v[128:131], v139 offset:24848
	ds_read_b128 v[108:111], v139 offset:8448
	ds_read_b128 v[112:115], v139 offset:8464
	ds_read_b128 v[116:119], v139 offset:16640
	ds_read_b128 v[120:123], v139 offset:16656
	ds_read_b64 v[178:179], v141 offset:41216
	ds_read_b128 v[170:173], v139 offset:33024
	ds_read_b128 v[174:177], v139 offset:33040
	ds_read_b128 v[100:103], v139 offset:256
	ds_read_b128 v[104:107], v139 offset:272
	v_pk_mul_f32 v[132:133], v[156:157], v[82:83] op_sel_hi:[1,0]
	v_pk_mul_f32 v[156:157], v[156:157], v[66:67] op_sel_hi:[1,0]
	v_pk_fma_f32 v[132:133], v[56:57], v[82:83], v[132:133] op_sel:[0,1,0]
	v_pk_mul_f32 v[56:57], v[56:57], v[66:67] op_sel:[0,1]
	v_pk_fma_f32 v[132:133], v[158:159], v[84:85], v[132:133] op_sel_hi:[1,0,1]
	v_pk_mul_f32 v[158:159], v[158:159], v[68:69] op_sel_hi:[1,0]
	v_pk_fma_f32 v[132:133], v[168:169], v[84:85], v[132:133] op_sel:[0,1,0]
	v_pk_mul_f32 v[168:169], v[168:169], v[68:69] op_sel:[0,1]
	v_pk_fma_f32 v[132:133], v[166:167], v[86:87], v[132:133] op_sel_hi:[1,0,1]
	v_pk_mul_f32 v[166:167], v[166:167], v[70:71] op_sel_hi:[1,0]
	v_pk_fma_f32 v[132:133], v[54:55], v[86:87], v[132:133] op_sel:[0,1,0]
	v_pk_mul_f32 v[54:55], v[54:55], v[70:71] op_sel:[0,1]
	v_pk_fma_f32 v[132:133], v[160:161], v[88:89], v[132:133] op_sel_hi:[1,0,1]
	v_pk_mul_f32 v[160:161], v[160:161], v[72:73] op_sel_hi:[1,0]
	v_pk_fma_f32 v[132:133], v[162:163], v[88:89], v[132:133] op_sel:[0,1,0]
	v_pk_mul_f32 v[162:163], v[162:163], v[72:73] op_sel:[0,1]
	v_pk_fma_f32 v[156:157], v[98:99], v[74:75], v[156:157] op_sel_hi:[1,0,1]
	v_pk_fma_f32 v[56:57], v[98:99], v[74:75], v[56:57] op_sel:[0,1,0]
	v_add_f32_dpp v132, v132, v132 quad_perm:[1,0,3,2] row_mask:0xf bank_mask:0xf bound_ctrl:1
	v_add_f32_dpp v133, v133, v133 quad_perm:[1,0,3,2] row_mask:0xf bank_mask:0xf bound_ctrl:1
	v_pk_fma_f32 v[158:159], v[98:99], v[76:77], v[158:159] op_sel_hi:[1,0,1]
	v_add_f32_dpp v132, v132, v132 quad_perm:[2,3,0,1] row_mask:0xf bank_mask:0xf bound_ctrl:1
	v_add_f32_dpp v133, v133, v133 quad_perm:[2,3,0,1] row_mask:0xf bank_mask:0xf bound_ctrl:1
	v_pk_fma_f32 v[168:169], v[98:99], v[76:77], v[168:169] op_sel:[0,1,0]
	v_add_f32_dpp v132, v132, v132 row_half_mirror row_mask:0xf bank_mask:0xf bound_ctrl:1
	v_add_f32_dpp v133, v133, v133 row_half_mirror row_mask:0xf bank_mask:0xf bound_ctrl:1
	v_pk_fma_f32 v[166:167], v[98:99], v[78:79], v[166:167] op_sel_hi:[1,0,1]
	v_pk_fma_f32 v[54:55], v[98:99], v[78:79], v[54:55] op_sel:[0,1,0]
	v_pk_fma_f32 v[160:161], v[98:99], v[80:81], v[160:161] op_sel_hi:[1,0,1]
	v_pk_fma_f32 v[162:163], v[98:99], v[80:81], v[162:163] op_sel:[0,1,0]
	v_pk_fma_f32 v[156:157], v[132:133], v[90:91], v[156:157] op_sel_hi:[1,0,1] neg_lo:[1,0,0] neg_hi:[1,0,0]
	v_pk_fma_f32 v[56:57], v[132:133], v[90:91], v[56:57] op_sel:[0,1,0] neg_lo:[1,0,0] neg_hi:[1,0,0]
	v_pk_mul_f32 v[134:135], v[156:157], v[58:59] op_sel_hi:[1,0]
	v_pk_fma_f32 v[158:159], v[132:133], v[92:93], v[158:159] op_sel_hi:[1,0,1] neg_lo:[1,0,0] neg_hi:[1,0,0]
	v_pk_fma_f32 v[134:135], v[56:57], v[58:59], v[134:135] op_sel:[0,1,0]
	v_pk_fma_f32 v[168:169], v[132:133], v[92:93], v[168:169] op_sel:[0,1,0] neg_lo:[1,0,0] neg_hi:[1,0,0]
	v_pk_fma_f32 v[134:135], v[158:159], v[60:61], v[134:135] op_sel_hi:[1,0,1]
	v_pk_fma_f32 v[166:167], v[132:133], v[94:95], v[166:167] op_sel_hi:[1,0,1] neg_lo:[1,0,0] neg_hi:[1,0,0]
	v_pk_fma_f32 v[134:135], v[168:169], v[60:61], v[134:135] op_sel:[0,1,0]
	v_pk_fma_f32 v[54:55], v[132:133], v[94:95], v[54:55] op_sel:[0,1,0] neg_lo:[1,0,0] neg_hi:[1,0,0]
	v_pk_fma_f32 v[134:135], v[166:167], v[62:63], v[134:135] op_sel_hi:[1,0,1]
	v_pk_fma_f32 v[160:161], v[132:133], v[96:97], v[160:161] op_sel_hi:[1,0,1] neg_lo:[1,0,0] neg_hi:[1,0,0]
	v_pk_fma_f32 v[134:135], v[54:55], v[62:63], v[134:135] op_sel:[0,1,0]
	v_pk_fma_f32 v[162:163], v[132:133], v[96:97], v[162:163] op_sel:[0,1,0] neg_lo:[1,0,0] neg_hi:[1,0,0]
	v_pk_fma_f32 v[134:135], v[160:161], v[64:65], v[134:135] op_sel_hi:[1,0,1]
	v_pk_fma_f32 v[134:135], v[162:163], v[64:65], v[134:135] op_sel:[0,1,0]
	s_waitcnt lgkmcnt(0)
; __device__ __forceinline__ float red8(float v) { v += dppf<DPP_X1>(v); v += dppf<DPP_X2>(v); v += dppf<DPP_HM>(v); return v; }
;     ...
;                 for (int j = 0; j < 8; ++j) {
;                     StepV nxt; { const int tn = (t8 + j + 1 < TC) ? t8 + j + 1 : t8 + j; SCAN_FETCH(nxt, tn); }
;                     asm volatile("" ::: "memory");
;                     f32x2 sa0 = S[0] * cur.qq[0][0] + S[1] * cur.qq[0][1], sa1 = S[2] * cur.qq[0][2] + S[3] * cur.qq[0][3], sa2 = S[4] * cur.qq[1][0] + S[5] * cur.qq[1][1], sa3 = S[6] * cur.qq[1][2] + S[7] * cur.qq[1][3];
;                     f32x2 tt[8];
; #pragma unroll
;                     for (int i = 0; i < 8; ++i) tt[i] = S[i] * cur.ww[i >> 2][i & 3] + cur.vv * cur.kx[i >> 2][i & 3];
;                     f32x2 sa = (sa0 + sa1) + (sa2 + sa3);
;                     { float sx = sa.x, sy = sa.y; asm volatile("" : "+v"(sx)); asm volatile("" : "+v"(sy)); sx = red8(sx); asm volatile("" : "+v"(sx)); sy = red8(sy); sa.x = -sx; sa.y = -sy; }
; #pragma unroll
;                     for (int i = 0; i < 8; ++i) S[i] = tt[i] + sa * cur.bb[i >> 2][i & 3];
;                     f32x2 oo = ((S[0] * cur.rr[0][0] + S[1] * cur.rr[0][1]) + (S[2] * cur.rr[0][2] + S[3] * cur.rr[0][3])) + ((S[4] * cur.rr[1][0] + S[5] * cur.rr[1][1]) + (S[6] * cur.rr[1][2] + S[7] * cur.rr[1][3]));
;                     { float ox = oo.x, oy = oo.y; asm volatile("" : "+v"(ox)); asm volatile("" : "+v"(oy)); ox = red8(ox); asm volatile("" : "+v"(ox)); oy = red8(oy); oo.x = ox; oo.y = oy; }
;                     if (kq == j) keep = oo;
;                     cur = nxt;
	ds_read_b128 v[82:85], v139 offset:25088
	ds_read_b128 v[86:89], v139 offset:25104
	ds_read_b128 v[66:69], v139 offset:8704
	ds_read_b128 v[70:73], v139 offset:8720
	ds_read_b128 v[74:77], v139 offset:16896
	ds_read_b128 v[78:81], v139 offset:16912
	ds_read_b64 v[98:99], v141 offset:41472
	ds_read_b128 v[90:93], v139 offset:33280
	ds_read_b128 v[94:97], v139 offset:33296
	ds_read_b128 v[58:61], v139 offset:512
	ds_read_b128 v[62:65], v139 offset:528
	v_pk_mul_f32 v[132:133], v[156:157], v[124:125] op_sel_hi:[1,0]
	v_pk_mul_f32 v[156:157], v[156:157], v[108:109] op_sel_hi:[1,0]
	v_add_f32_dpp v134, v134, v134 quad_perm:[1,0,3,2] row_mask:0xf bank_mask:0xf bound_ctrl:1
	v_add_f32_dpp v135, v135, v135 quad_perm:[1,0,3,2] row_mask:0xf bank_mask:0xf bound_ctrl:1
	v_pk_fma_f32 v[132:133], v[56:57], v[124:125], v[132:133] op_sel:[0,1,0]
	v_pk_mul_f32 v[56:57], v[56:57], v[108:109] op_sel:[0,1]
	v_pk_fma_f32 v[132:133], v[158:159], v[126:127], v[132:133] op_sel_hi:[1,0,1]
	v_pk_mul_f32 v[158:159], v[158:159], v[110:111] op_sel_hi:[1,0]
	v_add_f32_dpp v134, v134, v134 quad_perm:[2,3,0,1] row_mask:0xf bank_mask:0xf bound_ctrl:1
	v_add_f32_dpp v135, v135, v135 quad_perm:[2,3,0,1] row_mask:0xf bank_mask:0xf bound_ctrl:1
	v_pk_fma_f32 v[132:133], v[168:169], v[126:127], v[132:133] op_sel:[0,1,0]
	v_pk_mul_f32 v[168:169], v[168:169], v[110:111] op_sel:[0,1]
	v_pk_fma_f32 v[132:133], v[166:167], v[128:129], v[132:133] op_sel_hi:[1,0,1]
	v_pk_mul_f32 v[166:167], v[166:167], v[112:113] op_sel_hi:[1,0]
	v_add_f32_dpp v134, v134, v134 row_half_mirror row_mask:0xf bank_mask:0xf bound_ctrl:1
	v_add_f32_dpp v135, v135, v135 row_half_mirror row_mask:0xf bank_mask:0xf bound_ctrl:1
	v_pk_fma_f32 v[132:133], v[54:55], v[128:129], v[132:133] op_sel:[0,1,0]
	v_pk_mul_f32 v[54:55], v[54:55], v[112:113] op_sel:[0,1]
	v_pk_fma_f32 v[132:133], v[160:161], v[130:131], v[132:133] op_sel_hi:[1,0,1]
	v_pk_mul_f32 v[160:161], v[160:161], v[114:115] op_sel_hi:[1,0]
	v_cndmask_b32_e64 v136, v136, v134, s[2:3]
	v_cndmask_b32_e64 v137, v137, v135, s[2:3]
	v_pk_fma_f32 v[132:133], v[162:163], v[130:131], v[132:133] op_sel:[0,1,0]
	v_pk_mul_f32 v[162:163], v[162:163], v[114:115] op_sel:[0,1]
	v_pk_fma_f32 v[156:157], v[178:179], v[116:117], v[156:157] op_sel_hi:[1,0,1]
	v_pk_fma_f32 v[56:57], v[178:179], v[116:117], v[56:57] op_sel:[0,1,0]
	v_add_f32_dpp v132, v132, v132 quad_perm:[1,0,3,2] row_mask:0xf bank_mask:0xf bound_ctrl:1
	v_add_f32_dpp v133, v133, v133 quad_perm:[1,0,3,2] row_mask:0xf bank_mask:0xf bound_ctrl:1
	v_pk_fma_f32 v[158:159], v[178:179], v[118:119], v[158:159] op_sel_hi:[1,0,1]
	v_add_f32_dpp v132, v132, v132 quad_perm:[2,3,0,1] row_mask:0xf bank_mask:0xf bound_ctrl:1
	v_add_f32_dpp v133, v133, v133 quad_perm:[2,3,0,1] row_mask:0xf bank_mask:0xf bound_ctrl:1
	v_pk_fma_f32 v[168:169], v[178:179], v[118:119], v[168:169] op_sel:[0,1,0]
	v_add_f32_dpp v132, v132, v132 row_half_mirror row_mask:0xf bank_mask:0xf bound_ctrl:1
	v_add_f32_dpp v133, v133, v133 row_half_mirror row_mask:0xf bank_mask:0xf bound_ctrl:1
	v_pk_fma_f32 v[166:167], v[178:179], v[120:121], v[166:167] op_sel_hi:[1,0,1]
	v_pk_fma_f32 v[54:55], v[178:179], v[120:121], v[54:55] op_sel:[0,1,0]
	v_pk_fma_f32 v[160:161], v[178:179], v[122:123], v[160:161] op_sel_hi:[1,0,1]
	v_pk_fma_f32 v[162:163], v[178:179], v[122:123], v[162:163] op_sel:[0,1,0]
	v_pk_fma_f32 v[156:157], v[132:133], v[170:171], v[156:157] op_sel_hi:[1,0,1] neg_lo:[1,0,0] neg_hi:[1,0,0]
	v_pk_fma_f32 v[56:57], v[132:133], v[170:171], v[56:57] op_sel:[0,1,0] neg_lo:[1,0,0] neg_hi:[1,0,0]
	v_pk_mul_f32 v[134:135], v[156:157], v[100:101] op_sel_hi:[1,0]
	v_pk_fma_f32 v[158:159], v[132:133], v[172:173], v[158:159] op_sel_hi:[1,0,1] neg_lo:[1,0,0] neg_hi:[1,0,0]
	v_pk_fma_f32 v[134:135], v[56:57], v[100:101], v[134:135] op_sel:[0,1,0]
	v_pk_fma_f32 v[168:169], v[132:133], v[172:173], v[168:169] op_sel:[0,1,0] neg_lo:[1,0,0] neg_hi:[1,0,0]
	v_pk_fma_f32 v[134:135], v[158:159], v[102:103], v[134:135] op_sel_hi:[1,0,1]
	v_pk_fma_f32 v[166:167], v[132:133], v[174:175], v[166:167] op_sel_hi:[1,0,1] neg_lo:[1,0,0] neg_hi:[1,0,0]
	v_pk_fma_f32 v[134:135], v[168:169], v[102:103], v[134:135] op_sel:[0,1,0]
	v_pk_fma_f32 v[54:55], v[132:133], v[174:175], v[54:55] op_sel:[0,1,0] neg_lo:[1,0,0] neg_hi:[1,0,0]
	v_pk_fma_f32 v[134:135], v[166:167], v[104:105], v[134:135] op_sel_hi:[1,0,1]
	v_pk_fma_f32 v[160:161], v[132:133], v[176:177], v[160:161] op_sel_hi:[1,0,1] neg_lo:[1,0,0] neg_hi:[1,0,0]
	v_pk_fma_f32 v[134:135], v[54:55], v[104:105], v[134:135] op_sel:[0,1,0]
	v_pk_fma_f32 v[162:163], v[132:133], v[176:177], v[162:163] op_sel:[0,1,0] neg_lo:[1,0,0] neg_hi:[1,0,0]
	v_pk_fma_f32 v[134:135], v[160:161], v[106:107], v[134:135] op_sel_hi:[1,0,1]
	v_pk_fma_f32 v[134:135], v[162:163], v[106:107], v[134:135] op_sel:[0,1,0]
	s_waitcnt lgkmcnt(0)
; __device__ __forceinline__ float red8(float v) { v += dppf<DPP_X1>(v); v += dppf<DPP_X2>(v); v += dppf<DPP_HM>(v); return v; }
;     ...
;                 for (int j = 0; j < 8; ++j) {
;                     StepV nxt; { const int tn = (t8 + j + 1 < TC) ? t8 + j + 1 : t8 + j; SCAN_FETCH(nxt, tn); }
;                     asm volatile("" ::: "memory");
;                     f32x2 sa0 = S[0] * cur.qq[0][0] + S[1] * cur.qq[0][1], sa1 = S[2] * cur.qq[0][2] + S[3] * cur.qq[0][3], sa2 = S[4] * cur.qq[1][0] + S[5] * cur.qq[1][1], sa3 = S[6] * cur.qq[1][2] + S[7] * cur.qq[1][3];
;                     f32x2 tt[8];
; #pragma unroll
;                     for (int i = 0; i < 8; ++i) tt[i] = S[i] * cur.ww[i >> 2][i & 3] + cur.vv * cur.kx[i >> 2][i & 3];
;                     f32x2 sa = (sa0 + sa1) + (sa2 + sa3);
;                     { float sx = sa.x, sy = sa.y; asm volatile("" : "+v"(sx)); asm volatile("" : "+v"(sy)); sx = red8(sx); asm volatile("" : "+v"(sx)); sy = red8(sy); sa.x = -sx; sa.y = -sy; }
; #pragma unroll
;                     for (int i = 0; i < 8; ++i) S[i] = tt[i] + sa * cur.bb[i >> 2][i & 3];
;                     f32x2 oo = ((S[0] * cur.rr[0][0] + S[1] * cur.rr[0][1]) + (S[2] * cur.rr[0][2] + S[3] * cur.rr[0][3])) + ((S[4] * cur.rr[1][0] + S[5] * cur.rr[1][1]) + (S[6] * cur.rr[1][2] + S[7] * cur.rr[1][3]));
;                     { float ox = oo.x, oy = oo.y; asm volatile("" : "+v"(ox)); asm volatile("" : "+v"(oy)); ox = red8(ox); asm volatile("" : "+v"(ox)); oy = red8(oy); oo.x = ox; oo.y = oy; }
;                     if (kq == j) keep = oo;
;                     cur = nxt;
	ds_read_b128 v[124:127], v139 offset:25344
	ds_read_b128 v[128:131], v139 offset:25360
	ds_read_b128 v[108:111], v139 offset:8960
	ds_read_b128 v[112:115], v139 offset:8976
	ds_read_b128 v[116:119], v139 offset:17152
	ds_read_b128 v[120:123], v139 offset:17168
	ds_read_b64 v[178:179], v141 offset:41728
	ds_read_b128 v[170:173], v139 offset:33536
	ds_read_b128 v[174:177], v139 offset:33552
	ds_read_b128 v[100:103], v139 offset:768
	ds_read_b128 v[104:107], v139 offset:784
	v_pk_mul_f32 v[132:133], v[156:157], v[82:83] op_sel_hi:[1,0]
	v_pk_mul_f32 v[156:157], v[156:157], v[66:67] op_sel_hi:[1,0]
	v_add_f32_dpp v134, v134, v134 quad_perm:[1,0,3,2] row_mask:0xf bank_mask:0xf bound_ctrl:1
	v_add_f32_dpp v135, v135, v135 quad_perm:[1,0,3,2] row_mask:0xf bank_mask:0xf bound_ctrl:1
	v_pk_fma_f32 v[132:133], v[56:57], v[82:83], v[132:133] op_sel:[0,1,0]
	v_pk_mul_f32 v[56:57], v[56:57], v[66:67] op_sel:[0,1]
	v_pk_fma_f32 v[132:133], v[158:159], v[84:85], v[132:133] op_sel_hi:[1,0,1]
	v_pk_mul_f32 v[158:159], v[158:159], v[68:69] op_sel_hi:[1,0]
	v_add_f32_dpp v134, v134, v134 quad_perm:[2,3,0,1] row_mask:0xf bank_mask:0xf bound_ctrl:1
	v_add_f32_dpp v135, v135, v135 quad_perm:[2,3,0,1] row_mask:0xf bank_mask:0xf bound_ctrl:1
	v_pk_fma_f32 v[132:133], v[168:169], v[84:85], v[132:133] op_sel:[0,1,0]
	v_pk_mul_f32 v[168:169], v[168:169], v[68:69] op_sel:[0,1]
	v_pk_fma_f32 v[132:133], v[166:167], v[86:87], v[132:133] op_sel_hi:[1,0,1]
	v_pk_mul_f32 v[166:167], v[166:167], v[70:71] op_sel_hi:[1,0]
	v_add_f32_dpp v134, v134, v134 row_half_mirror row_mask:0xf bank_mask:0xf bound_ctrl:1
	v_add_f32_dpp v135, v135, v135 row_half_mirror row_mask:0xf bank_mask:0xf bound_ctrl:1
	v_pk_fma_f32 v[132:133], v[54:55], v[86:87], v[132:133] op_sel:[0,1,0]
	v_pk_mul_f32 v[54:55], v[54:55], v[70:71] op_sel:[0,1]
	v_pk_fma_f32 v[132:133], v[160:161], v[88:89], v[132:133] op_sel_hi:[1,0,1]
	v_pk_mul_f32 v[160:161], v[160:161], v[72:73] op_sel_hi:[1,0]
	v_cndmask_b32_e64 v136, v136, v134, s[4:5]
	v_cndmask_b32_e64 v137, v137, v135, s[4:5]
	v_pk_fma_f32 v[132:133], v[162:163], v[88:89], v[132:133] op_sel:[0,1,0]
	v_pk_mul_f32 v[162:163], v[162:163], v[72:73] op_sel:[0,1]
	v_pk_fma_f32 v[156:157], v[98:99], v[74:75], v[156:157] op_sel_hi:[1,0,1]
	v_pk_fma_f32 v[56:57], v[98:99], v[74:75], v[56:57] op_sel:[0,1,0]
	v_add_f32_dpp v132, v132, v132 quad_perm:[1,0,3,2] row_mask:0xf bank_mask:0xf bound_ctrl:1
	v_add_f32_dpp v133, v133, v133 quad_perm:[1,0,3,2] row_mask:0xf bank_mask:0xf bound_ctrl:1
	v_pk_fma_f32 v[158:159], v[98:99], v[76:77], v[158:159] op_sel_hi:[1,0,1]
	v_add_f32_dpp v132, v132, v132 quad_perm:[2,3,0,1] row_mask:0xf bank_mask:0xf bound_ctrl:1
	v_add_f32_dpp v133, v133, v133 quad_perm:[2,3,0,1] row_mask:0xf bank_mask:0xf bound_ctrl:1
	v_pk_fma_f32 v[168:169], v[98:99], v[76:77], v[168:169] op_sel:[0,1,0]
	v_add_f32_dpp v132, v132, v132 row_half_mirror row_mask:0xf bank_mask:0xf bound_ctrl:1
	v_add_f32_dpp v133, v133, v133 row_half_mirror row_mask:0xf bank_mask:0xf bound_ctrl:1
	v_pk_fma_f32 v[166:167], v[98:99], v[78:79], v[166:167] op_sel_hi:[1,0,1]
	v_pk_fma_f32 v[54:55], v[98:99], v[78:79], v[54:55] op_sel:[0,1,0]
	v_pk_fma_f32 v[160:161], v[98:99], v[80:81], v[160:161] op_sel_hi:[1,0,1]
	v_pk_fma_f32 v[162:163], v[98:99], v[80:81], v[162:163] op_sel:[0,1,0]
	v_pk_fma_f32 v[156:157], v[132:133], v[90:91], v[156:157] op_sel_hi:[1,0,1] neg_lo:[1,0,0] neg_hi:[1,0,0]
	v_pk_fma_f32 v[56:57], v[132:133], v[90:91], v[56:57] op_sel:[0,1,0] neg_lo:[1,0,0] neg_hi:[1,0,0]
	v_pk_mul_f32 v[134:135], v[156:157], v[58:59] op_sel_hi:[1,0]
	v_pk_fma_f32 v[158:159], v[132:133], v[92:93], v[158:159] op_sel_hi:[1,0,1] neg_lo:[1,0,0] neg_hi:[1,0,0]
	v_pk_fma_f32 v[134:135], v[56:57], v[58:59], v[134:135] op_sel:[0,1,0]
	v_pk_fma_f32 v[168:169], v[132:133], v[92:93], v[168:169] op_sel:[0,1,0] neg_lo:[1,0,0] neg_hi:[1,0,0]
	v_pk_fma_f32 v[134:135], v[158:159], v[60:61], v[134:135] op_sel_hi:[1,0,1]
	v_pk_fma_f32 v[166:167], v[132:133], v[94:95], v[166:167] op_sel_hi:[1,0,1] neg_lo:[1,0,0] neg_hi:[1,0,0]
	v_pk_fma_f32 v[134:135], v[168:169], v[60:61], v[134:135] op_sel:[0,1,0]
	v_pk_fma_f32 v[54:55], v[132:133], v[94:95], v[54:55] op_sel:[0,1,0] neg_lo:[1,0,0] neg_hi:[1,0,0]
	v_pk_fma_f32 v[134:135], v[166:167], v[62:63], v[134:135] op_sel_hi:[1,0,1]
	v_pk_fma_f32 v[160:161], v[132:133], v[96:97], v[160:161] op_sel_hi:[1,0,1] neg_lo:[1,0,0] neg_hi:[1,0,0]
	v_pk_fma_f32 v[134:135], v[54:55], v[62:63], v[134:135] op_sel:[0,1,0]
	v_pk_fma_f32 v[162:163], v[132:133], v[96:97], v[162:163] op_sel:[0,1,0] neg_lo:[1,0,0] neg_hi:[1,0,0]
	v_pk_fma_f32 v[134:135], v[160:161], v[64:65], v[134:135] op_sel_hi:[1,0,1]
	v_pk_fma_f32 v[134:135], v[162:163], v[64:65], v[134:135] op_sel:[0,1,0]
	s_waitcnt lgkmcnt(0)
; __device__ __forceinline__ float red8(float v) { v += dppf<DPP_X1>(v); v += dppf<DPP_X2>(v); v += dppf<DPP_HM>(v); return v; }
;     ...
;                 for (int j = 0; j < 8; ++j) {
;                     StepV nxt; { const int tn = (t8 + j + 1 < TC) ? t8 + j + 1 : t8 + j; SCAN_FETCH(nxt, tn); }
;                     asm volatile("" ::: "memory");
;                     f32x2 sa0 = S[0] * cur.qq[0][0] + S[1] * cur.qq[0][1], sa1 = S[2] * cur.qq[0][2] + S[3] * cur.qq[0][3], sa2 = S[4] * cur.qq[1][0] + S[5] * cur.qq[1][1], sa3 = S[6] * cur.qq[1][2] + S[7] * cur.qq[1][3];
;                     f32x2 tt[8];
; #pragma unroll
;                     for (int i = 0; i < 8; ++i) tt[i] = S[i] * cur.ww[i >> 2][i & 3] + cur.vv * cur.kx[i >> 2][i & 3];
;                     f32x2 sa = (sa0 + sa1) + (sa2 + sa3);
;                     { float sx = sa.x, sy = sa.y; asm volatile("" : "+v"(sx)); asm volatile("" : "+v"(sy)); sx = red8(sx); asm volatile("" : "+v"(sx)); sy = red8(sy); sa.x = -sx; sa.y = -sy; }
; #pragma unroll
;                     for (int i = 0; i < 8; ++i) S[i] = tt[i] + sa * cur.bb[i >> 2][i & 3];
;                     f32x2 oo = ((S[0] * cur.rr[0][0] + S[1] * cur.rr[0][1]) + (S[2] * cur.rr[0][2] + S[3] * cur.rr[0][3])) + ((S[4] * cur.rr[1][0] + S[5] * cur.rr[1][1]) + (S[6] * cur.rr[1][2] + S[7] * cur.rr[1][3]));
;                     { float ox = oo.x, oy = oo.y; asm volatile("" : "+v"(ox)); asm volatile("" : "+v"(oy)); ox = red8(ox); asm volatile("" : "+v"(ox)); oy = red8(oy); oo.x = ox; oo.y = oy; }
;                     if (kq == j) keep = oo;
;                     cur = nxt;
	ds_read_b128 v[82:85], v139 offset:25600
	ds_read_b128 v[86:89], v139 offset:25616
	ds_read_b128 v[66:69], v139 offset:9216
	ds_read_b128 v[70:73], v139 offset:9232
	ds_read_b128 v[74:77], v139 offset:17408
	ds_read_b128 v[78:81], v139 offset:17424
	ds_read_b64 v[98:99], v141 offset:41984
	ds_read_b128 v[90:93], v139 offset:33792
	ds_read_b128 v[94:97], v139 offset:33808
	ds_read_b128 v[58:61], v139 offset:1024
	ds_read_b128 v[62:65], v139 offset:1040
	v_pk_mul_f32 v[132:133], v[156:157], v[124:125] op_sel_hi:[1,0]
	v_pk_mul_f32 v[156:157], v[156:157], v[108:109] op_sel_hi:[1,0]
	v_add_f32_dpp v134, v134, v134 quad_perm:[1,0,3,2] row_mask:0xf bank_mask:0xf bound_ctrl:1
	v_add_f32_dpp v135, v135, v135 quad_perm:[1,0,3,2] row_mask:0xf bank_mask:0xf bound_ctrl:1
	v_pk_fma_f32 v[132:133], v[56:57], v[124:125], v[132:133] op_sel:[0,1,0]
	v_pk_mul_f32 v[56:57], v[56:57], v[108:109] op_sel:[0,1]
	v_pk_fma_f32 v[132:133], v[158:159], v[126:127], v[132:133] op_sel_hi:[1,0,1]
	v_pk_mul_f32 v[158:159], v[158:159], v[110:111] op_sel_hi:[1,0]
	v_add_f32_dpp v134, v134, v134 quad_perm:[2,3,0,1] row_mask:0xf bank_mask:0xf bound_ctrl:1
	v_add_f32_dpp v135, v135, v135 quad_perm:[2,3,0,1] row_mask:0xf bank_mask:0xf bound_ctrl:1
	v_pk_fma_f32 v[132:133], v[168:169], v[126:127], v[132:133] op_sel:[0,1,0]
	v_pk_mul_f32 v[168:169], v[168:169], v[110:111] op_sel:[0,1]
	v_pk_fma_f32 v[132:133], v[166:167], v[128:129], v[132:133] op_sel_hi:[1,0,1]
	v_pk_mul_f32 v[166:167], v[166:167], v[112:113] op_sel_hi:[1,0]
	v_add_f32_dpp v134, v134, v134 row_half_mirror row_mask:0xf bank_mask:0xf bound_ctrl:1
	v_add_f32_dpp v135, v135, v135 row_half_mirror row_mask:0xf bank_mask:0xf bound_ctrl:1
	v_pk_fma_f32 v[132:133], v[54:55], v[128:129], v[132:133] op_sel:[0,1,0]
	v_pk_mul_f32 v[54:55], v[54:55], v[112:113] op_sel:[0,1]
	v_pk_fma_f32 v[132:133], v[160:161], v[130:131], v[132:133] op_sel_hi:[1,0,1]
	v_pk_mul_f32 v[160:161], v[160:161], v[114:115] op_sel_hi:[1,0]
	v_cndmask_b32_e64 v136, v136, v134, s[6:7]
	v_cndmask_b32_e64 v137, v137, v135, s[6:7]
	v_pk_fma_f32 v[132:133], v[162:163], v[130:131], v[132:133] op_sel:[0,1,0]
	v_pk_mul_f32 v[162:163], v[162:163], v[114:115] op_sel:[0,1]
	v_pk_fma_f32 v[156:157], v[178:179], v[116:117], v[156:157] op_sel_hi:[1,0,1]
	v_pk_fma_f32 v[56:57], v[178:179], v[116:117], v[56:57] op_sel:[0,1,0]
	v_add_f32_dpp v132, v132, v132 quad_perm:[1,0,3,2] row_mask:0xf bank_mask:0xf bound_ctrl:1
	v_add_f32_dpp v133, v133, v133 quad_perm:[1,0,3,2] row_mask:0xf bank_mask:0xf bound_ctrl:1
	v_pk_fma_f32 v[158:159], v[178:179], v[118:119], v[158:159] op_sel_hi:[1,0,1]
	v_add_f32_dpp v132, v132, v132 quad_perm:[2,3,0,1] row_mask:0xf bank_mask:0xf bound_ctrl:1
	v_add_f32_dpp v133, v133, v133 quad_perm:[2,3,0,1] row_mask:0xf bank_mask:0xf bound_ctrl:1
	v_pk_fma_f32 v[168:169], v[178:179], v[118:119], v[168:169] op_sel:[0,1,0]
	v_add_f32_dpp v132, v132, v132 row_half_mirror row_mask:0xf bank_mask:0xf bound_ctrl:1
	v_add_f32_dpp v133, v133, v133 row_half_mirror row_mask:0xf bank_mask:0xf bound_ctrl:1
	v_pk_fma_f32 v[166:167], v[178:179], v[120:121], v[166:167] op_sel_hi:[1,0,1]
	v_pk_fma_f32 v[54:55], v[178:179], v[120:121], v[54:55] op_sel:[0,1,0]
	v_pk_fma_f32 v[160:161], v[178:179], v[122:123], v[160:161] op_sel_hi:[1,0,1]
	v_pk_fma_f32 v[162:163], v[178:179], v[122:123], v[162:163] op_sel:[0,1,0]
	v_pk_fma_f32 v[156:157], v[132:133], v[170:171], v[156:157] op_sel_hi:[1,0,1] neg_lo:[1,0,0] neg_hi:[1,0,0]
	v_pk_fma_f32 v[56:57], v[132:133], v[170:171], v[56:57] op_sel:[0,1,0] neg_lo:[1,0,0] neg_hi:[1,0,0]
	v_pk_mul_f32 v[134:135], v[156:157], v[100:101] op_sel_hi:[1,0]
	v_pk_fma_f32 v[158:159], v[132:133], v[172:173], v[158:159] op_sel_hi:[1,0,1] neg_lo:[1,0,0] neg_hi:[1,0,0]
	v_pk_fma_f32 v[134:135], v[56:57], v[100:101], v[134:135] op_sel:[0,1,0]
	v_pk_fma_f32 v[168:169], v[132:133], v[172:173], v[168:169] op_sel:[0,1,0] neg_lo:[1,0,0] neg_hi:[1,0,0]
	v_pk_fma_f32 v[134:135], v[158:159], v[102:103], v[134:135] op_sel_hi:[1,0,1]
	v_pk_fma_f32 v[166:167], v[132:133], v[174:175], v[166:167] op_sel_hi:[1,0,1] neg_lo:[1,0,0] neg_hi:[1,0,0]
	v_pk_fma_f32 v[134:135], v[168:169], v[102:103], v[134:135] op_sel:[0,1,0]
	v_pk_fma_f32 v[54:55], v[132:133], v[174:175], v[54:55] op_sel:[0,1,0] neg_lo:[1,0,0] neg_hi:[1,0,0]
	v_pk_fma_f32 v[134:135], v[166:167], v[104:105], v[134:135] op_sel_hi:[1,0,1]
	v_pk_fma_f32 v[160:161], v[132:133], v[176:177], v[160:161] op_sel_hi:[1,0,1] neg_lo:[1,0,0] neg_hi:[1,0,0]
	v_pk_fma_f32 v[134:135], v[54:55], v[104:105], v[134:135] op_sel:[0,1,0]
	v_pk_fma_f32 v[162:163], v[132:133], v[176:177], v[162:163] op_sel:[0,1,0] neg_lo:[1,0,0] neg_hi:[1,0,0]
	v_pk_fma_f32 v[134:135], v[160:161], v[106:107], v[134:135] op_sel_hi:[1,0,1]
	v_pk_fma_f32 v[134:135], v[162:163], v[106:107], v[134:135] op_sel:[0,1,0]
	s_waitcnt lgkmcnt(0)
; __device__ __forceinline__ float red8(float v) { v += dppf<DPP_X1>(v); v += dppf<DPP_X2>(v); v += dppf<DPP_HM>(v); return v; }
;     ...
;                 for (int j = 0; j < 8; ++j) {
;                     StepV nxt; { const int tn = (t8 + j + 1 < TC) ? t8 + j + 1 : t8 + j; SCAN_FETCH(nxt, tn); }
;                     asm volatile("" ::: "memory");
;                     f32x2 sa0 = S[0] * cur.qq[0][0] + S[1] * cur.qq[0][1], sa1 = S[2] * cur.qq[0][2] + S[3] * cur.qq[0][3], sa2 = S[4] * cur.qq[1][0] + S[5] * cur.qq[1][1], sa3 = S[6] * cur.qq[1][2] + S[7] * cur.qq[1][3];
;                     f32x2 tt[8];
; #pragma unroll
;                     for (int i = 0; i < 8; ++i) tt[i] = S[i] * cur.ww[i >> 2][i & 3] + cur.vv * cur.kx[i >> 2][i & 3];
;                     f32x2 sa = (sa0 + sa1) + (sa2 + sa3);
;                     { float sx = sa.x, sy = sa.y; asm volatile("" : "+v"(sx)); asm volatile("" : "+v"(sy)); sx = red8(sx); asm volatile("" : "+v"(sx)); sy = red8(sy); sa.x = -sx; sa.y = -sy; }
; #pragma unroll
;                     for (int i = 0; i < 8; ++i) S[i] = tt[i] + sa * cur.bb[i >> 2][i & 3];
;                     f32x2 oo = ((S[0] * cur.rr[0][0] + S[1] * cur.rr[0][1]) + (S[2] * cur.rr[0][2] + S[3] * cur.rr[0][3])) + ((S[4] * cur.rr[1][0] + S[5] * cur.rr[1][1]) + (S[6] * cur.rr[1][2] + S[7] * cur.rr[1][3]));
;                     { float ox = oo.x, oy = oo.y; asm volatile("" : "+v"(ox)); asm volatile("" : "+v"(oy)); ox = red8(ox); asm volatile("" : "+v"(ox)); oy = red8(oy); oo.x = ox; oo.y = oy; }
;                     if (kq == j) keep = oo;
;                     cur = nxt;
	ds_read_b128 v[124:127], v139 offset:25856
	ds_read_b128 v[128:131], v139 offset:25872
	ds_read_b128 v[108:111], v139 offset:9472
	ds_read_b128 v[112:115], v139 offset:9488
	ds_read_b128 v[116:119], v139 offset:17664
	ds_read_b128 v[120:123], v139 offset:17680
	ds_read_b64 v[178:179], v141 offset:42240
	ds_read_b128 v[170:173], v139 offset:34048
	ds_read_b128 v[174:177], v139 offset:34064
	ds_read_b128 v[100:103], v139 offset:1280
	ds_read_b128 v[104:107], v139 offset:1296
	v_pk_mul_f32 v[132:133], v[156:157], v[82:83] op_sel_hi:[1,0]
	v_pk_mul_f32 v[156:157], v[156:157], v[66:67] op_sel_hi:[1,0]
	v_add_f32_dpp v134, v134, v134 quad_perm:[1,0,3,2] row_mask:0xf bank_mask:0xf bound_ctrl:1
	v_add_f32_dpp v135, v135, v135 quad_perm:[1,0,3,2] row_mask:0xf bank_mask:0xf bound_ctrl:1
	v_pk_fma_f32 v[132:133], v[56:57], v[82:83], v[132:133] op_sel:[0,1,0]
	v_pk_mul_f32 v[56:57], v[56:57], v[66:67] op_sel:[0,1]
	v_pk_fma_f32 v[132:133], v[158:159], v[84:85], v[132:133] op_sel_hi:[1,0,1]
	v_pk_mul_f32 v[158:159], v[158:159], v[68:69] op_sel_hi:[1,0]
	v_add_f32_dpp v134, v134, v134 quad_perm:[2,3,0,1] row_mask:0xf bank_mask:0xf bound_ctrl:1
	v_add_f32_dpp v135, v135, v135 quad_perm:[2,3,0,1] row_mask:0xf bank_mask:0xf bound_ctrl:1
	v_pk_fma_f32 v[132:133], v[168:169], v[84:85], v[132:133] op_sel:[0,1,0]
	v_pk_mul_f32 v[168:169], v[168:169], v[68:69] op_sel:[0,1]
	v_pk_fma_f32 v[132:133], v[166:167], v[86:87], v[132:133] op_sel_hi:[1,0,1]
	v_pk_mul_f32 v[166:167], v[166:167], v[70:71] op_sel_hi:[1,0]
	v_add_f32_dpp v134, v134, v134 row_half_mirror row_mask:0xf bank_mask:0xf bound_ctrl:1
	v_add_f32_dpp v135, v135, v135 row_half_mirror row_mask:0xf bank_mask:0xf bound_ctrl:1
	v_pk_fma_f32 v[132:133], v[54:55], v[86:87], v[132:133] op_sel:[0,1,0]
	v_pk_mul_f32 v[54:55], v[54:55], v[70:71] op_sel:[0,1]
	v_pk_fma_f32 v[132:133], v[160:161], v[88:89], v[132:133] op_sel_hi:[1,0,1]
	v_pk_mul_f32 v[160:161], v[160:161], v[72:73] op_sel_hi:[1,0]
	v_cndmask_b32_e64 v136, v136, v134, s[8:9]
	v_cndmask_b32_e64 v137, v137, v135, s[8:9]
	v_pk_fma_f32 v[132:133], v[162:163], v[88:89], v[132:133] op_sel:[0,1,0]
	v_pk_mul_f32 v[162:163], v[162:163], v[72:73] op_sel:[0,1]
	v_pk_fma_f32 v[156:157], v[98:99], v[74:75], v[156:157] op_sel_hi:[1,0,1]
	v_pk_fma_f32 v[56:57], v[98:99], v[74:75], v[56:57] op_sel:[0,1,0]
	v_add_f32_dpp v132, v132, v132 quad_perm:[1,0,3,2] row_mask:0xf bank_mask:0xf bound_ctrl:1
	v_add_f32_dpp v133, v133, v133 quad_perm:[1,0,3,2] row_mask:0xf bank_mask:0xf bound_ctrl:1
	v_pk_fma_f32 v[158:159], v[98:99], v[76:77], v[158:159] op_sel_hi:[1,0,1]
	v_add_f32_dpp v132, v132, v132 quad_perm:[2,3,0,1] row_mask:0xf bank_mask:0xf bound_ctrl:1
	v_add_f32_dpp v133, v133, v133 quad_perm:[2,3,0,1] row_mask:0xf bank_mask:0xf bound_ctrl:1
	v_pk_fma_f32 v[168:169], v[98:99], v[76:77], v[168:169] op_sel:[0,1,0]
	v_add_f32_dpp v132, v132, v132 row_half_mirror row_mask:0xf bank_mask:0xf bound_ctrl:1
	v_add_f32_dpp v133, v133, v133 row_half_mirror row_mask:0xf bank_mask:0xf bound_ctrl:1
	v_pk_fma_f32 v[166:167], v[98:99], v[78:79], v[166:167] op_sel_hi:[1,0,1]
	v_pk_fma_f32 v[54:55], v[98:99], v[78:79], v[54:55] op_sel:[0,1,0]
	v_pk_fma_f32 v[160:161], v[98:99], v[80:81], v[160:161] op_sel_hi:[1,0,1]
	v_pk_fma_f32 v[162:163], v[98:99], v[80:81], v[162:163] op_sel:[0,1,0]
	v_pk_fma_f32 v[156:157], v[132:133], v[90:91], v[156:157] op_sel_hi:[1,0,1] neg_lo:[1,0,0] neg_hi:[1,0,0]
	v_pk_fma_f32 v[56:57], v[132:133], v[90:91], v[56:57] op_sel:[0,1,0] neg_lo:[1,0,0] neg_hi:[1,0,0]
	v_pk_mul_f32 v[134:135], v[156:157], v[58:59] op_sel_hi:[1,0]
	v_pk_fma_f32 v[158:159], v[132:133], v[92:93], v[158:159] op_sel_hi:[1,0,1] neg_lo:[1,0,0] neg_hi:[1,0,0]
	v_pk_fma_f32 v[134:135], v[56:57], v[58:59], v[134:135] op_sel:[0,1,0]
	v_pk_fma_f32 v[168:169], v[132:133], v[92:93], v[168:169] op_sel:[0,1,0] neg_lo:[1,0,0] neg_hi:[1,0,0]
	v_pk_fma_f32 v[134:135], v[158:159], v[60:61], v[134:135] op_sel_hi:[1,0,1]
	v_pk_fma_f32 v[166:167], v[132:133], v[94:95], v[166:167] op_sel_hi:[1,0,1] neg_lo:[1,0,0] neg_hi:[1,0,0]
	v_pk_fma_f32 v[134:135], v[168:169], v[60:61], v[134:135] op_sel:[0,1,0]
	v_pk_fma_f32 v[54:55], v[132:133], v[94:95], v[54:55] op_sel:[0,1,0] neg_lo:[1,0,0] neg_hi:[1,0,0]
	v_pk_fma_f32 v[134:135], v[166:167], v[62:63], v[134:135] op_sel_hi:[1,0,1]
	v_pk_fma_f32 v[160:161], v[132:133], v[96:97], v[160:161] op_sel_hi:[1,0,1] neg_lo:[1,0,0] neg_hi:[1,0,0]
	v_pk_fma_f32 v[134:135], v[54:55], v[62:63], v[134:135] op_sel:[0,1,0]
	v_pk_fma_f32 v[162:163], v[132:133], v[96:97], v[162:163] op_sel:[0,1,0] neg_lo:[1,0,0] neg_hi:[1,0,0]
	v_pk_fma_f32 v[134:135], v[160:161], v[64:65], v[134:135] op_sel_hi:[1,0,1]
	v_pk_fma_f32 v[134:135], v[162:163], v[64:65], v[134:135] op_sel:[0,1,0]
	s_waitcnt lgkmcnt(0)
; __device__ __forceinline__ float red8(float v) { v += dppf<DPP_X1>(v); v += dppf<DPP_X2>(v); v += dppf<DPP_HM>(v); return v; }
;     ...
;                 for (int j = 0; j < 8; ++j) {
;                     StepV nxt; { const int tn = (t8 + j + 1 < TC) ? t8 + j + 1 : t8 + j; SCAN_FETCH(nxt, tn); }
;                     asm volatile("" ::: "memory");
;                     f32x2 sa0 = S[0] * cur.qq[0][0] + S[1] * cur.qq[0][1], sa1 = S[2] * cur.qq[0][2] + S[3] * cur.qq[0][3], sa2 = S[4] * cur.qq[1][0] + S[5] * cur.qq[1][1], sa3 = S[6] * cur.qq[1][2] + S[7] * cur.qq[1][3];
;                     f32x2 tt[8];
; #pragma unroll
;                     for (int i = 0; i < 8; ++i) tt[i] = S[i] * cur.ww[i >> 2][i & 3] + cur.vv * cur.kx[i >> 2][i & 3];
;                     f32x2 sa = (sa0 + sa1) + (sa2 + sa3);
;                     { float sx = sa.x, sy = sa.y; asm volatile("" : "+v"(sx)); asm volatile("" : "+v"(sy)); sx = red8(sx); asm volatile("" : "+v"(sx)); sy = red8(sy); sa.x = -sx; sa.y = -sy; }
; #pragma unroll
;                     for (int i = 0; i < 8; ++i) S[i] = tt[i] + sa * cur.bb[i >> 2][i & 3];
;                     f32x2 oo = ((S[0] * cur.rr[0][0] + S[1] * cur.rr[0][1]) + (S[2] * cur.rr[0][2] + S[3] * cur.rr[0][3])) + ((S[4] * cur.rr[1][0] + S[5] * cur.rr[1][1]) + (S[6] * cur.rr[1][2] + S[7] * cur.rr[1][3]));
;                     { float ox = oo.x, oy = oo.y; asm volatile("" : "+v"(ox)); asm volatile("" : "+v"(oy)); ox = red8(ox); asm volatile("" : "+v"(ox)); oy = red8(oy); oo.x = ox; oo.y = oy; }
;                     if (kq == j) keep = oo;
;                     cur = nxt;
	ds_read_b128 v[82:85], v139 offset:26112
	ds_read_b128 v[86:89], v139 offset:26128
	ds_read_b128 v[66:69], v139 offset:9728
	ds_read_b128 v[70:73], v139 offset:9744
	ds_read_b128 v[74:77], v139 offset:17920
	ds_read_b128 v[78:81], v139 offset:17936
	ds_read_b64 v[98:99], v141 offset:42496
	ds_read_b128 v[90:93], v139 offset:34304
	ds_read_b128 v[94:97], v139 offset:34320
	ds_read_b128 v[58:61], v139 offset:1536
	ds_read_b128 v[62:65], v139 offset:1552
	v_pk_mul_f32 v[132:133], v[156:157], v[124:125] op_sel_hi:[1,0]
	v_pk_mul_f32 v[156:157], v[156:157], v[108:109] op_sel_hi:[1,0]
	v_add_f32_dpp v134, v134, v134 quad_perm:[1,0,3,2] row_mask:0xf bank_mask:0xf bound_ctrl:1
	v_add_f32_dpp v135, v135, v135 quad_perm:[1,0,3,2] row_mask:0xf bank_mask:0xf bound_ctrl:1
	v_pk_fma_f32 v[132:133], v[56:57], v[124:125], v[132:133] op_sel:[0,1,0]
	v_pk_mul_f32 v[56:57], v[56:57], v[108:109] op_sel:[0,1]
	v_pk_fma_f32 v[132:133], v[158:159], v[126:127], v[132:133] op_sel_hi:[1,0,1]
	v_pk_mul_f32 v[158:159], v[158:159], v[110:111] op_sel_hi:[1,0]
	v_add_f32_dpp v134, v134, v134 quad_perm:[2,3,0,1] row_mask:0xf bank_mask:0xf bound_ctrl:1
	v_add_f32_dpp v135, v135, v135 quad_perm:[2,3,0,1] row_mask:0xf bank_mask:0xf bound_ctrl:1
	v_pk_fma_f32 v[132:133], v[168:169], v[126:127], v[132:133] op_sel:[0,1,0]
	v_pk_mul_f32 v[168:169], v[168:169], v[110:111] op_sel:[0,1]
	v_pk_fma_f32 v[132:133], v[166:167], v[128:129], v[132:133] op_sel_hi:[1,0,1]
	v_pk_mul_f32 v[166:167], v[166:167], v[112:113] op_sel_hi:[1,0]
	v_add_f32_dpp v134, v134, v134 row_half_mirror row_mask:0xf bank_mask:0xf bound_ctrl:1
	v_add_f32_dpp v135, v135, v135 row_half_mirror row_mask:0xf bank_mask:0xf bound_ctrl:1
	v_pk_fma_f32 v[132:133], v[54:55], v[128:129], v[132:133] op_sel:[0,1,0]
	v_pk_mul_f32 v[54:55], v[54:55], v[112:113] op_sel:[0,1]
	v_pk_fma_f32 v[132:133], v[160:161], v[130:131], v[132:133] op_sel_hi:[1,0,1]
	v_pk_mul_f32 v[160:161], v[160:161], v[114:115] op_sel_hi:[1,0]
	v_cndmask_b32_e64 v136, v136, v134, s[10:11]
	v_cndmask_b32_e64 v137, v137, v135, s[10:11]
	v_pk_fma_f32 v[132:133], v[162:163], v[130:131], v[132:133] op_sel:[0,1,0]
	v_pk_mul_f32 v[162:163], v[162:163], v[114:115] op_sel:[0,1]
	v_pk_fma_f32 v[156:157], v[178:179], v[116:117], v[156:157] op_sel_hi:[1,0,1]
	v_pk_fma_f32 v[56:57], v[178:179], v[116:117], v[56:57] op_sel:[0,1,0]
	v_add_f32_dpp v132, v132, v132 quad_perm:[1,0,3,2] row_mask:0xf bank_mask:0xf bound_ctrl:1
	v_add_f32_dpp v133, v133, v133 quad_perm:[1,0,3,2] row_mask:0xf bank_mask:0xf bound_ctrl:1
	v_pk_fma_f32 v[158:159], v[178:179], v[118:119], v[158:159] op_sel_hi:[1,0,1]
	v_add_f32_dpp v132, v132, v132 quad_perm:[2,3,0,1] row_mask:0xf bank_mask:0xf bound_ctrl:1
	v_add_f32_dpp v133, v133, v133 quad_perm:[2,3,0,1] row_mask:0xf bank_mask:0xf bound_ctrl:1
	v_pk_fma_f32 v[168:169], v[178:179], v[118:119], v[168:169] op_sel:[0,1,0]
	v_add_f32_dpp v132, v132, v132 row_half_mirror row_mask:0xf bank_mask:0xf bound_ctrl:1
	v_add_f32_dpp v133, v133, v133 row_half_mirror row_mask:0xf bank_mask:0xf bound_ctrl:1
	v_pk_fma_f32 v[166:167], v[178:179], v[120:121], v[166:167] op_sel_hi:[1,0,1]
	v_pk_fma_f32 v[54:55], v[178:179], v[120:121], v[54:55] op_sel:[0,1,0]
	v_pk_fma_f32 v[160:161], v[178:179], v[122:123], v[160:161] op_sel_hi:[1,0,1]
	v_pk_fma_f32 v[162:163], v[178:179], v[122:123], v[162:163] op_sel:[0,1,0]
	v_pk_fma_f32 v[156:157], v[132:133], v[170:171], v[156:157] op_sel_hi:[1,0,1] neg_lo:[1,0,0] neg_hi:[1,0,0]
	v_pk_fma_f32 v[56:57], v[132:133], v[170:171], v[56:57] op_sel:[0,1,0] neg_lo:[1,0,0] neg_hi:[1,0,0]
	v_pk_mul_f32 v[134:135], v[156:157], v[100:101] op_sel_hi:[1,0]
	v_pk_fma_f32 v[158:159], v[132:133], v[172:173], v[158:159] op_sel_hi:[1,0,1] neg_lo:[1,0,0] neg_hi:[1,0,0]
	v_pk_fma_f32 v[134:135], v[56:57], v[100:101], v[134:135] op_sel:[0,1,0]
	v_pk_fma_f32 v[168:169], v[132:133], v[172:173], v[168:169] op_sel:[0,1,0] neg_lo:[1,0,0] neg_hi:[1,0,0]
	v_pk_fma_f32 v[134:135], v[158:159], v[102:103], v[134:135] op_sel_hi:[1,0,1]
	v_pk_fma_f32 v[166:167], v[132:133], v[174:175], v[166:167] op_sel_hi:[1,0,1] neg_lo:[1,0,0] neg_hi:[1,0,0]
	v_pk_fma_f32 v[134:135], v[168:169], v[102:103], v[134:135] op_sel:[0,1,0]
	v_pk_fma_f32 v[54:55], v[132:133], v[174:175], v[54:55] op_sel:[0,1,0] neg_lo:[1,0,0] neg_hi:[1,0,0]
	v_pk_fma_f32 v[134:135], v[166:167], v[104:105], v[134:135] op_sel_hi:[1,0,1]
	v_pk_fma_f32 v[160:161], v[132:133], v[176:177], v[160:161] op_sel_hi:[1,0,1] neg_lo:[1,0,0] neg_hi:[1,0,0]
	v_pk_fma_f32 v[134:135], v[54:55], v[104:105], v[134:135] op_sel:[0,1,0]
	v_pk_fma_f32 v[162:163], v[132:133], v[176:177], v[162:163] op_sel:[0,1,0] neg_lo:[1,0,0] neg_hi:[1,0,0]
	v_pk_fma_f32 v[134:135], v[160:161], v[106:107], v[134:135] op_sel_hi:[1,0,1]
	v_pk_fma_f32 v[134:135], v[162:163], v[106:107], v[134:135] op_sel:[0,1,0]
	s_waitcnt lgkmcnt(0)
; __device__ __forceinline__ float red8(float v) { v += dppf<DPP_X1>(v); v += dppf<DPP_X2>(v); v += dppf<DPP_HM>(v); return v; }
;     ...
;                 for (int j = 0; j < 8; ++j) {
;                     StepV nxt; { const int tn = (t8 + j + 1 < TC) ? t8 + j + 1 : t8 + j; SCAN_FETCH(nxt, tn); }
;                     asm volatile("" ::: "memory");
;                     f32x2 sa0 = S[0] * cur.qq[0][0] + S[1] * cur.qq[0][1], sa1 = S[2] * cur.qq[0][2] + S[3] * cur.qq[0][3], sa2 = S[4] * cur.qq[1][0] + S[5] * cur.qq[1][1], sa3 = S[6] * cur.qq[1][2] + S[7] * cur.qq[1][3];
;                     f32x2 tt[8];
; #pragma unroll
;                     for (int i = 0; i < 8; ++i) tt[i] = S[i] * cur.ww[i >> 2][i & 3] + cur.vv * cur.kx[i >> 2][i & 3];
;                     f32x2 sa = (sa0 + sa1) + (sa2 + sa3);
;                     { float sx = sa.x, sy = sa.y; asm volatile("" : "+v"(sx)); asm volatile("" : "+v"(sy)); sx = red8(sx); asm volatile("" : "+v"(sx)); sy = red8(sy); sa.x = -sx; sa.y = -sy; }
; #pragma unroll
;                     for (int i = 0; i < 8; ++i) S[i] = tt[i] + sa * cur.bb[i >> 2][i & 3];
;                     f32x2 oo = ((S[0] * cur.rr[0][0] + S[1] * cur.rr[0][1]) + (S[2] * cur.rr[0][2] + S[3] * cur.rr[0][3])) + ((S[4] * cur.rr[1][0] + S[5] * cur.rr[1][1]) + (S[6] * cur.rr[1][2] + S[7] * cur.rr[1][3]));
;                     { float ox = oo.x, oy = oo.y; asm volatile("" : "+v"(ox)); asm volatile("" : "+v"(oy)); ox = red8(ox); asm volatile("" : "+v"(ox)); oy = red8(oy); oo.x = ox; oo.y = oy; }
;                     if (kq == j) keep = oo;
;                     cur = nxt;
	ds_read_b128 v[124:127], v139 offset:26368
	ds_read_b128 v[128:131], v139 offset:26384
	ds_read_b128 v[108:111], v139 offset:9984
	ds_read_b128 v[112:115], v139 offset:10000
	ds_read_b128 v[116:119], v139 offset:18176
	ds_read_b128 v[120:123], v139 offset:18192
	ds_read_b64 v[178:179], v141 offset:42752
	ds_read_b128 v[170:173], v139 offset:34560
	ds_read_b128 v[174:177], v139 offset:34576
	ds_read_b128 v[100:103], v139 offset:1792
	ds_read_b128 v[104:107], v139 offset:1808
	v_pk_mul_f32 v[132:133], v[156:157], v[82:83] op_sel_hi:[1,0]
	v_pk_mul_f32 v[156:157], v[156:157], v[66:67] op_sel_hi:[1,0]
	v_add_f32_dpp v134, v134, v134 quad_perm:[1,0,3,2] row_mask:0xf bank_mask:0xf bound_ctrl:1
	v_add_f32_dpp v135, v135, v135 quad_perm:[1,0,3,2] row_mask:0xf bank_mask:0xf bound_ctrl:1
	v_pk_fma_f32 v[132:133], v[56:57], v[82:83], v[132:133] op_sel:[0,1,0]
	v_pk_mul_f32 v[56:57], v[56:57], v[66:67] op_sel:[0,1]
	v_pk_fma_f32 v[132:133], v[158:159], v[84:85], v[132:133] op_sel_hi:[1,0,1]
	v_pk_mul_f32 v[158:159], v[158:159], v[68:69] op_sel_hi:[1,0]
	v_add_f32_dpp v134, v134, v134 quad_perm:[2,3,0,1] row_mask:0xf bank_mask:0xf bound_ctrl:1
	v_add_f32_dpp v135, v135, v135 quad_perm:[2,3,0,1] row_mask:0xf bank_mask:0xf bound_ctrl:1
	v_pk_fma_f32 v[132:133], v[168:169], v[84:85], v[132:133] op_sel:[0,1,0]
	v_pk_mul_f32 v[168:169], v[168:169], v[68:69] op_sel:[0,1]
	v_pk_fma_f32 v[132:133], v[166:167], v[86:87], v[132:133] op_sel_hi:[1,0,1]
	v_pk_mul_f32 v[166:167], v[166:167], v[70:71] op_sel_hi:[1,0]
	v_add_f32_dpp v134, v134, v134 row_half_mirror row_mask:0xf bank_mask:0xf bound_ctrl:1
	v_add_f32_dpp v135, v135, v135 row_half_mirror row_mask:0xf bank_mask:0xf bound_ctrl:1
	v_pk_fma_f32 v[132:133], v[54:55], v[86:87], v[132:133] op_sel:[0,1,0]
	v_pk_mul_f32 v[54:55], v[54:55], v[70:71] op_sel:[0,1]
	v_pk_fma_f32 v[132:133], v[160:161], v[88:89], v[132:133] op_sel_hi:[1,0,1]
	v_pk_mul_f32 v[160:161], v[160:161], v[72:73] op_sel_hi:[1,0]
	v_cndmask_b32_e64 v136, v136, v134, s[12:13]
	v_cndmask_b32_e64 v137, v137, v135, s[12:13]
	v_pk_fma_f32 v[132:133], v[162:163], v[88:89], v[132:133] op_sel:[0,1,0]
	v_pk_mul_f32 v[162:163], v[162:163], v[72:73] op_sel:[0,1]
	v_pk_fma_f32 v[156:157], v[98:99], v[74:75], v[156:157] op_sel_hi:[1,0,1]
	v_pk_fma_f32 v[56:57], v[98:99], v[74:75], v[56:57] op_sel:[0,1,0]
	v_add_f32_dpp v132, v132, v132 quad_perm:[1,0,3,2] row_mask:0xf bank_mask:0xf bound_ctrl:1
	v_add_f32_dpp v133, v133, v133 quad_perm:[1,0,3,2] row_mask:0xf bank_mask:0xf bound_ctrl:1
	v_pk_fma_f32 v[158:159], v[98:99], v[76:77], v[158:159] op_sel_hi:[1,0,1]
	v_add_f32_dpp v132, v132, v132 quad_perm:[2,3,0,1] row_mask:0xf bank_mask:0xf bound_ctrl:1
	v_add_f32_dpp v133, v133, v133 quad_perm:[2,3,0,1] row_mask:0xf bank_mask:0xf bound_ctrl:1
	v_pk_fma_f32 v[168:169], v[98:99], v[76:77], v[168:169] op_sel:[0,1,0]
	v_add_f32_dpp v132, v132, v132 row_half_mirror row_mask:0xf bank_mask:0xf bound_ctrl:1
	v_add_f32_dpp v133, v133, v133 row_half_mirror row_mask:0xf bank_mask:0xf bound_ctrl:1
	v_pk_fma_f32 v[166:167], v[98:99], v[78:79], v[166:167] op_sel_hi:[1,0,1]
	v_pk_fma_f32 v[54:55], v[98:99], v[78:79], v[54:55] op_sel:[0,1,0]
	v_pk_fma_f32 v[160:161], v[98:99], v[80:81], v[160:161] op_sel_hi:[1,0,1]
	v_pk_fma_f32 v[162:163], v[98:99], v[80:81], v[162:163] op_sel:[0,1,0]
	v_pk_fma_f32 v[156:157], v[132:133], v[90:91], v[156:157] op_sel_hi:[1,0,1] neg_lo:[1,0,0] neg_hi:[1,0,0]
	v_pk_fma_f32 v[56:57], v[132:133], v[90:91], v[56:57] op_sel:[0,1,0] neg_lo:[1,0,0] neg_hi:[1,0,0]
	v_pk_mul_f32 v[134:135], v[156:157], v[58:59] op_sel_hi:[1,0]
	v_pk_fma_f32 v[158:159], v[132:133], v[92:93], v[158:159] op_sel_hi:[1,0,1] neg_lo:[1,0,0] neg_hi:[1,0,0]
	v_pk_fma_f32 v[134:135], v[56:57], v[58:59], v[134:135] op_sel:[0,1,0]
	v_pk_fma_f32 v[168:169], v[132:133], v[92:93], v[168:169] op_sel:[0,1,0] neg_lo:[1,0,0] neg_hi:[1,0,0]
	v_pk_fma_f32 v[134:135], v[158:159], v[60:61], v[134:135] op_sel_hi:[1,0,1]
	v_pk_fma_f32 v[166:167], v[132:133], v[94:95], v[166:167] op_sel_hi:[1,0,1] neg_lo:[1,0,0] neg_hi:[1,0,0]
	v_pk_fma_f32 v[134:135], v[168:169], v[60:61], v[134:135] op_sel:[0,1,0]
	v_pk_fma_f32 v[54:55], v[132:133], v[94:95], v[54:55] op_sel:[0,1,0] neg_lo:[1,0,0] neg_hi:[1,0,0]
	v_pk_fma_f32 v[134:135], v[166:167], v[62:63], v[134:135] op_sel_hi:[1,0,1]
	v_pk_fma_f32 v[160:161], v[132:133], v[96:97], v[160:161] op_sel_hi:[1,0,1] neg_lo:[1,0,0] neg_hi:[1,0,0]
	v_pk_fma_f32 v[134:135], v[54:55], v[62:63], v[134:135] op_sel:[0,1,0]
	v_pk_fma_f32 v[162:163], v[132:133], v[96:97], v[162:163] op_sel:[0,1,0] neg_lo:[1,0,0] neg_hi:[1,0,0]
	v_pk_fma_f32 v[134:135], v[160:161], v[64:65], v[134:135] op_sel_hi:[1,0,1]
	v_pk_fma_f32 v[134:135], v[162:163], v[64:65], v[134:135] op_sel:[0,1,0]
	s_waitcnt lgkmcnt(0)
; #define LAS __attribute__((address_space(3)))
; __device__ __forceinline__ float red8(float v) { v += dppf<DPP_X1>(v); v += dppf<DPP_X2>(v); v += dppf<DPP_HM>(v); return v; }
;     ...
;                 for (int j = 0; j < 8; ++j) {
;                     StepV nxt; { const int tn = (t8 + j + 1 < TC) ? t8 + j + 1 : t8 + j; SCAN_FETCH(nxt, tn); }
;                     asm volatile("" ::: "memory");
;                     f32x2 sa0 = S[0] * cur.qq[0][0] + S[1] * cur.qq[0][1], sa1 = S[2] * cur.qq[0][2] + S[3] * cur.qq[0][3], sa2 = S[4] * cur.qq[1][0] + S[5] * cur.qq[1][1], sa3 = S[6] * cur.qq[1][2] + S[7] * cur.qq[1][3];
;                     f32x2 tt[8];
; #pragma unroll
;                     for (int i = 0; i < 8; ++i) tt[i] = S[i] * cur.ww[i >> 2][i & 3] + cur.vv * cur.kx[i >> 2][i & 3];
;                     f32x2 sa = (sa0 + sa1) + (sa2 + sa3);
;                     { float sx = sa.x, sy = sa.y; asm volatile("" : "+v"(sx)); asm volatile("" : "+v"(sy)); sx = red8(sx); asm volatile("" : "+v"(sx)); sy = red8(sy); sa.x = -sx; sa.y = -sy; }
; #pragma unroll
;                     for (int i = 0; i < 8; ++i) S[i] = tt[i] + sa * cur.bb[i >> 2][i & 3];
;                     f32x2 oo = ((S[0] * cur.rr[0][0] + S[1] * cur.rr[0][1]) + (S[2] * cur.rr[0][2] + S[3] * cur.rr[0][3])) + ((S[4] * cur.rr[1][0] + S[5] * cur.rr[1][1]) + (S[6] * cur.rr[1][2] + S[7] * cur.rr[1][3]));
;                     { float ox = oo.x, oy = oo.y; asm volatile("" : "+v"(ox)); asm volatile("" : "+v"(oy)); ox = red8(ox); asm volatile("" : "+v"(ox)); oy = red8(oy); oo.x = ox; oo.y = oy; }
;                     if (kq == j) keep = oo;
;                     cur = nxt;
;                 }
;                 *(LAS f32x2*)(sO + (t8 + kq) * 64 + 2 * vp) = keep;
;             }
	ds_read_b128 v[82:85], v139 offset:26624
	ds_read_b128 v[86:89], v139 offset:26640
	ds_read_b128 v[66:69], v139 offset:10240
	ds_read_b128 v[70:73], v139 offset:10256
	ds_read_b128 v[74:77], v139 offset:18432
	ds_read_b128 v[78:81], v139 offset:18448
	ds_read_b64 v[98:99], v141 offset:43008
	ds_read_b128 v[90:93], v139 offset:34816
	ds_read_b128 v[94:97], v139 offset:34832
	ds_read_b128 v[58:61], v139 offset:2048
	ds_read_b128 v[62:65], v139 offset:2064
	v_pk_mul_f32 v[132:133], v[156:157], v[124:125] op_sel_hi:[1,0]
	v_pk_mul_f32 v[156:157], v[156:157], v[108:109] op_sel_hi:[1,0]
	v_add_f32_dpp v134, v134, v134 quad_perm:[1,0,3,2] row_mask:0xf bank_mask:0xf bound_ctrl:1
	v_add_f32_dpp v135, v135, v135 quad_perm:[1,0,3,2] row_mask:0xf bank_mask:0xf bound_ctrl:1
	v_pk_fma_f32 v[132:133], v[56:57], v[124:125], v[132:133] op_sel:[0,1,0]
	v_pk_mul_f32 v[56:57], v[56:57], v[108:109] op_sel:[0,1]
	v_pk_fma_f32 v[132:133], v[158:159], v[126:127], v[132:133] op_sel_hi:[1,0,1]
	v_pk_mul_f32 v[158:159], v[158:159], v[110:111] op_sel_hi:[1,0]
	v_add_f32_dpp v134, v134, v134 quad_perm:[2,3,0,1] row_mask:0xf bank_mask:0xf bound_ctrl:1
	v_add_f32_dpp v135, v135, v135 quad_perm:[2,3,0,1] row_mask:0xf bank_mask:0xf bound_ctrl:1
	v_pk_fma_f32 v[132:133], v[168:169], v[126:127], v[132:133] op_sel:[0,1,0]
	v_pk_mul_f32 v[168:169], v[168:169], v[110:111] op_sel:[0,1]
	v_pk_fma_f32 v[132:133], v[166:167], v[128:129], v[132:133] op_sel_hi:[1,0,1]
	v_pk_mul_f32 v[166:167], v[166:167], v[112:113] op_sel_hi:[1,0]
	v_add_f32_dpp v134, v134, v134 row_half_mirror row_mask:0xf bank_mask:0xf bound_ctrl:1
	v_add_f32_dpp v135, v135, v135 row_half_mirror row_mask:0xf bank_mask:0xf bound_ctrl:1
	v_pk_fma_f32 v[132:133], v[54:55], v[128:129], v[132:133] op_sel:[0,1,0]
	v_pk_mul_f32 v[54:55], v[54:55], v[112:113] op_sel:[0,1]
	v_pk_fma_f32 v[132:133], v[160:161], v[130:131], v[132:133] op_sel_hi:[1,0,1]
	v_pk_mul_f32 v[160:161], v[160:161], v[114:115] op_sel_hi:[1,0]
	v_cndmask_b32_e64 v136, v136, v134, s[14:15]
	v_cndmask_b32_e64 v137, v137, v135, s[14:15]
	v_pk_fma_f32 v[132:133], v[162:163], v[130:131], v[132:133] op_sel:[0,1,0]
	v_pk_mul_f32 v[162:163], v[162:163], v[114:115] op_sel:[0,1]
	v_pk_fma_f32 v[156:157], v[178:179], v[116:117], v[156:157] op_sel_hi:[1,0,1]
	v_pk_fma_f32 v[56:57], v[178:179], v[116:117], v[56:57] op_sel:[0,1,0]
	v_add_f32_dpp v132, v132, v132 quad_perm:[1,0,3,2] row_mask:0xf bank_mask:0xf bound_ctrl:1
	v_add_f32_dpp v133, v133, v133 quad_perm:[1,0,3,2] row_mask:0xf bank_mask:0xf bound_ctrl:1
	v_pk_fma_f32 v[158:159], v[178:179], v[118:119], v[158:159] op_sel_hi:[1,0,1]
	v_add_f32_dpp v132, v132, v132 quad_perm:[2,3,0,1] row_mask:0xf bank_mask:0xf bound_ctrl:1
	v_add_f32_dpp v133, v133, v133 quad_perm:[2,3,0,1] row_mask:0xf bank_mask:0xf bound_ctrl:1
	v_pk_fma_f32 v[168:169], v[178:179], v[118:119], v[168:169] op_sel:[0,1,0]
	v_add_f32_dpp v132, v132, v132 row_half_mirror row_mask:0xf bank_mask:0xf bound_ctrl:1
	v_add_f32_dpp v133, v133, v133 row_half_mirror row_mask:0xf bank_mask:0xf bound_ctrl:1
	v_pk_fma_f32 v[166:167], v[178:179], v[120:121], v[166:167] op_sel_hi:[1,0,1]
	v_pk_fma_f32 v[54:55], v[178:179], v[120:121], v[54:55] op_sel:[0,1,0]
	v_pk_fma_f32 v[160:161], v[178:179], v[122:123], v[160:161] op_sel_hi:[1,0,1]
	v_pk_fma_f32 v[162:163], v[178:179], v[122:123], v[162:163] op_sel:[0,1,0]
	v_pk_fma_f32 v[156:157], v[132:133], v[170:171], v[156:157] op_sel_hi:[1,0,1] neg_lo:[1,0,0] neg_hi:[1,0,0]
	v_pk_fma_f32 v[56:57], v[132:133], v[170:171], v[56:57] op_sel:[0,1,0] neg_lo:[1,0,0] neg_hi:[1,0,0]
	v_pk_mul_f32 v[134:135], v[156:157], v[100:101] op_sel_hi:[1,0]
	v_pk_fma_f32 v[158:159], v[132:133], v[172:173], v[158:159] op_sel_hi:[1,0,1] neg_lo:[1,0,0] neg_hi:[1,0,0]
	v_pk_fma_f32 v[134:135], v[56:57], v[100:101], v[134:135] op_sel:[0,1,0]
	v_pk_fma_f32 v[168:169], v[132:133], v[172:173], v[168:169] op_sel:[0,1,0] neg_lo:[1,0,0] neg_hi:[1,0,0]
	v_pk_fma_f32 v[134:135], v[158:159], v[102:103], v[134:135] op_sel_hi:[1,0,1]
	v_pk_fma_f32 v[166:167], v[132:133], v[174:175], v[166:167] op_sel_hi:[1,0,1] neg_lo:[1,0,0] neg_hi:[1,0,0]
	v_pk_fma_f32 v[134:135], v[168:169], v[102:103], v[134:135] op_sel:[0,1,0]
	v_pk_fma_f32 v[54:55], v[132:133], v[174:175], v[54:55] op_sel:[0,1,0] neg_lo:[1,0,0] neg_hi:[1,0,0]
	v_pk_fma_f32 v[134:135], v[166:167], v[104:105], v[134:135] op_sel_hi:[1,0,1]
	v_pk_fma_f32 v[160:161], v[132:133], v[176:177], v[160:161] op_sel_hi:[1,0,1] neg_lo:[1,0,0] neg_hi:[1,0,0]
	v_pk_fma_f32 v[134:135], v[54:55], v[104:105], v[134:135] op_sel:[0,1,0]
	v_pk_fma_f32 v[162:163], v[132:133], v[176:177], v[162:163] op_sel:[0,1,0] neg_lo:[1,0,0] neg_hi:[1,0,0]
	v_pk_fma_f32 v[134:135], v[160:161], v[106:107], v[134:135] op_sel_hi:[1,0,1]
	v_pk_fma_f32 v[134:135], v[162:163], v[106:107], v[134:135] op_sel:[0,1,0]
	s_nop 1
	v_add_f32_dpp v134, v134, v134 quad_perm:[1,0,3,2] row_mask:0xf bank_mask:0xf bound_ctrl:1
	v_add_f32_dpp v135, v135, v135 quad_perm:[1,0,3,2] row_mask:0xf bank_mask:0xf bound_ctrl:1
	s_nop 0
	v_add_f32_dpp v134, v134, v134 quad_perm:[2,3,0,1] row_mask:0xf bank_mask:0xf bound_ctrl:1
	v_add_f32_dpp v135, v135, v135 quad_perm:[2,3,0,1] row_mask:0xf bank_mask:0xf bound_ctrl:1
	s_nop 0
	v_add_f32_dpp v134, v134, v134 row_half_mirror row_mask:0xf bank_mask:0xf bound_ctrl:1
	v_add_f32_dpp v135, v135, v135 row_half_mirror row_mask:0xf bank_mask:0xf bound_ctrl:1
	v_add_u32_e32 v139, 0x800, v139
	v_cndmask_b32_e64 v136, v136, v134, s[16:17]
	v_cndmask_b32_e64 v137, v137, v135, s[16:17]
	v_add_u32_e32 v141, 0x800, v141
	ds_write_b64 v180, v[136:137]
	v_add_u32_e32 v180, 0x800, v180
	s_add_i32 s24, s24, 1
	s_cmp_lt_u32 s24, 4
	s_cbranch_scc1 .Lscan4_loop
